# cross-lane move of the substitution via v_permlane16_swap instead of ds_bpermute (no LDS round trip on the per-sub-chunk critical chain)
# baseline (speedup 1.0000x reference)
.Lmy_f_main:
	s_cmpk_ge_u32 s62, 0x100
	s_cbranch_scc1 .Lmy_f_hlp
	s_cmp_lg_u32 s65, 0
	s_cbranch_scc1 .Lmy_ck_nz
	v_mov_b32_e32 v208, 0
	v_mov_b32_e32 v209, 0
	v_mov_b32_e32 v210, 0
	v_mov_b32_e32 v211, 0
	v_mov_b32_e32 v212, 0
	v_mov_b32_e32 v213, 0
	v_mov_b32_e32 v214, 0
	v_mov_b32_e32 v215, 0
	v_mov_b32_e32 v216, 0
	v_mov_b32_e32 v217, 0
	v_mov_b32_e32 v218, 0
	v_mov_b32_e32 v219, 0
	v_mov_b32_e32 v220, 0
	v_mov_b32_e32 v221, 0
	v_mov_b32_e32 v222, 0
	v_mov_b32_e32 v223, 0
	v_mov_b32_e32 v204, 0
	v_mov_b32_e32 v205, 0
	v_mov_b32_e32 v206, 0
	v_mov_b32_e32 v207, 0
	v_lshlrev_b32_e32 v0, 4, v224
	v_xor_b32_e32 v1, v224, v234
	v_lshlrev_b32_e32 v1, 4, v1
	v_lshlrev_b32_e32 v2, 4, v234
	v_add_u32_e32 v2, 0x2000, v2
	v_mov_b32_e32 v72, 0x2600
	v_mov_b32_e32 v73, 0x2500
	v_mov_b32_e32 v74, 0x2510
	v_mov_b32_e32 v75, 0x2590
	v_cmp_eq_u32_e64 s[96:97], 0, v234
	v_and_b32_e32 v76, 1, v234
	v_lshrrev_b32_e32 v77, 1, v234
	v_cndmask_b32_e64 v3, v72, v73, s[96:97]
	v_cmp_eq_u32_e64 s[96:97], 1, v234
	v_and_b32_e32 v78, 1, v234
	v_add_u32_e32 v79, 2, v77
	v_cndmask_b32_e64 v4, v72, v74, s[96:97]
	v_cndmask_b32_e64 v5, v72, v75, s[96:97]
	v_lshlrev_b32_e32 v76, 10, v76
	v_lshl_add_u32 v76, v233, 2, v76
	v_add_u32_e32 v8, s62, v76
	v_lshlrev_b32_e32 v76, 9, v234
	v_lshl_add_u32 v76, v233, 2, v76
	v_add_u32_e32 v9, s62, v76
	v_lshl_add_u32 v6, v79, 4, v233
	v_xor_b32_e32 v6, v6, v79
	v_lshlrev_b32_e32 v6, 4, v6
	v_lshl_add_u32 v6, v78, 3, v6
	v_add_u32_e32 v6, 0x2100, v6
	v_lshl_add_u32 v7, v78, 4, v233
	v_xor_b32_e32 v7, v7, v78
	v_lshlrev_b32_e32 v7, 4, v7
	v_lshl_add_u32 v7, v77, 3, v7
	v_add_u32_e32 v7, 0x2100, v7
	v_add_u32_e32 v232, 48, v224
	v_and_b32_e32 v232, 63, v232
	v_lshlrev_b32_e32 v232, 2, v232
.Lmy_ck_nz:
	s_mov_b32 s100, 0xe000
	s_cmp_eq_u32 s23, 0
	s_cselect_b32 s100, 0x1c000, s100
	s_mov_b32 s101, 0x12e00
	s_cselect_b32 s101, 0x22100, s101
	s_lshl_b32 s96, s23, 13
	s_add_i32 s97, s96, 0x18000
	s_add_i32 s96, s96, 0xa000
	v_add_u32_e32 v225, s100, v1
	v_add_u32_e32 v236, s100, v0
	v_add_u32_e32 v226, s100, v2
	v_add_u32_e32 v227, s100, v3
	v_add_u32_e32 v228, s100, v4
	v_add_u32_e32 v229, s100, v5
	v_add_u32_e32 v237, s100, v6
	v_add_u32_e32 v238, s100, v7
	v_add_u32_e32 v230, s96, v8
	v_add_u32_e32 v239, s96, v9
	v_add_u32_e32 v231, s97, v8
	v_add_u32_e32 v26, s101, v1
	v_add_u32_e32 v27, s101, v0
	v_add_u32_e32 v28, s101, v2
	v_add_u32_e32 v29, s101, v3
	v_add_u32_e32 v30, s101, v4
	v_add_u32_e32 v31, s101, v5
	v_add_u32_e32 v32, s101, v6
	v_add_u32_e32 v33, s101, v7
	ds_read_b64 v[80:81], v237
	ds_read_b64 v[82:83], v238
	ds_read_b32 v84, v230
	ds_read_b32 v85, v230 offset:256
	ds_read_b32 v86, v230 offset:512
	ds_read_b32 v87, v230 offset:768
	ds_read_b32 v36, v239
	ds_read_b32 v37, v239 offset:256
	ds_read_b128 v[88:91], v225
	ds_read_b128 v[92:95], v225 offset:1024
	ds_read_b128 v[96:99], v225 offset:2048
	ds_read_b128 v[100:103], v225 offset:3072
	ds_read_b32 v104, v227 offset:4
	ds_read_b32 v105, v227 offset:76
	ds_read_b64 v[106:107], v227 offset:8
	ds_read_b64 v[108:109], v227 offset:40
	ds_read_b32 v126, v229 offset:4
	ds_read_b32 v127, v229 offset:76
	ds_read_b64 v[128:129], v229 offset:8
	ds_read_b64 v[130:131], v229 offset:40
	ds_read_b64 v[110:111], v228
	ds_read_b64 v[112:113], v228 offset:32
	ds_read_b64 v[114:115], v228 offset:64
	ds_read_b64 v[116:117], v228 offset:96
	ds_read_b64 v[118:119], v228 offset:8
	ds_read_b64 v[120:121], v228 offset:40
	ds_read_b64 v[122:123], v228 offset:72
	ds_read_b64 v[124:125], v228 offset:104
	s_waitcnt lgkmcnt(15)
	v_mfma_f32_16x16x4_f32 v[240:243], v80, v36, 0
	v_mfma_f32_16x16x4_f32 v[240:243], v81, v37, v[240:243]
	v_mfma_f32_16x16x4_f32 v[240:243], v88, v208, v[240:243]
	ds_read_b128 v[184:187], v236 offset:4096
	ds_read_b128 v[188:191], v236 offset:5120
	v_mfma_f32_16x16x4_f32 v[244:247], v89, v209, 0
	ds_read_b128 v[192:195], v236 offset:6144
	ds_read_b128 v[196:199], v236 offset:7168
	v_mfma_f32_16x16x4_f32 v[240:243], v90, v210, v[240:243]
	ds_read_b64 v[132:133], v237 offset:9984
	ds_read_b64 v[134:135], v238 offset:9984
	v_mfma_f32_16x16x4_f32 v[244:247], v91, v211, v[244:247]
	ds_read_b32 v136, v230 offset:2048
	ds_read_b32 v137, v230 offset:2304
	v_mfma_f32_16x16x4_f32 v[240:243], v92, v212, v[240:243]
	ds_read_b32 v138, v230 offset:2560
	ds_read_b32 v139, v230 offset:2816
	v_mfma_f32_16x16x4_f32 v[244:247], v93, v213, v[244:247]
	ds_read_b32 v38, v239 offset:2048
	ds_read_b32 v39, v239 offset:2304
	v_mfma_f32_16x16x4_f32 v[240:243], v94, v214, v[240:243]
	ds_read_b128 v[140:143], v225 offset:9984
	ds_read_b128 v[144:147], v225 offset:11008
	v_mfma_f32_16x16x4_f32 v[244:247], v95, v215, v[244:247]
	ds_read_b128 v[148:151], v225 offset:12032
	ds_read_b128 v[152:155], v225 offset:13056
	v_mfma_f32_16x16x4_f32 v[240:243], v96, v216, v[240:243]
	ds_read_b32 v156, v227 offset:9988
	ds_read_b32 v157, v227 offset:10060
	v_mfma_f32_16x16x4_f32 v[244:247], v97, v217, v[244:247]
	ds_read_b64 v[158:159], v227 offset:9992
	ds_read_b64 v[160:161], v227 offset:10024
	v_mfma_f32_16x16x4_f32 v[240:243], v98, v218, v[240:243]
	ds_read_b32 v178, v229 offset:9988
	ds_read_b32 v179, v229 offset:10060
	v_mfma_f32_16x16x4_f32 v[244:247], v99, v219, v[244:247]
	ds_read_b64 v[180:181], v229 offset:9992
	ds_read_b64 v[182:183], v229 offset:10024
	v_mfma_f32_16x16x4_f32 v[240:243], v100, v220, v[240:243]
	ds_read_b64 v[162:163], v228 offset:9984
	ds_read_b64 v[164:165], v228 offset:10016
	v_mfma_f32_16x16x4_f32 v[244:247], v101, v221, v[244:247]
	ds_read_b64 v[166:167], v228 offset:10048
	ds_read_b64 v[168:169], v228 offset:10080
	v_mfma_f32_16x16x4_f32 v[240:243], v102, v222, v[240:243]
	ds_read_b64 v[170:171], v228 offset:9992
	ds_read_b64 v[172:173], v228 offset:10024
	v_mfma_f32_16x16x4_f32 v[244:247], v103, v223, v[244:247]
	ds_read_b64 v[174:175], v228 offset:10056
	ds_read_b64 v[176:177], v228 offset:10088
	s_nop 7
	v_pk_add_f32 v[240:241], v[240:241], v[244:245]
	v_pk_add_f32 v[242:243], v[242:243], v[246:247]
	v_fmac_f32_e32 v241, v104, v240
	s_waitcnt lgkmcnt(13)
	v_pk_fma_f32 v[242:243], v[106:107], v[240:241], v[242:243] op_sel:[0,0,0] op_sel_hi:[1,0,1]
	v_pk_fma_f32 v[242:243], v[108:109], v[240:241], v[242:243] op_sel:[0,1,0] op_sel_hi:[1,1,1]
	v_fmac_f32_e32 v243, v105, v242
	v_mov_b32_e32 v44, v240
	v_mov_b32_e32 v45, v241
	v_mov_b32_e32 v60, v242
	v_mov_b32_e32 v61, v243
	v_permlane16_swap_b32_e32 v204, v44
	v_permlane16_swap_b32_e32 v205, v45
	v_permlane16_swap_b32_e32 v206, v60
	v_permlane16_swap_b32_e32 v207, v61
	ds_read_b128 v[88:91], v226
	ds_read_b128 v[92:95], v226 offset:64
	ds_read_b128 v[96:99], v226 offset:128
	ds_read_b128 v[100:103], v226 offset:192
	v_mfma_f32_16x16x4_f32 v[72:75], v132, v38, 0
	v_mfma_f32_16x16x4_f32 v[72:75], v133, v39, v[72:75]
	v_pk_fma_f32 v[240:241], v[110:111], v[204:205], v[240:241] op_sel:[0,0,0] op_sel_hi:[1,0,1]
	v_pk_fma_f32 v[240:241], v[112:113], v[204:205], v[240:241] op_sel:[0,1,0] op_sel_hi:[1,1,1]
	v_pk_fma_f32 v[240:241], v[114:115], v[206:207], v[240:241] op_sel:[0,0,0] op_sel_hi:[1,0,1]
	v_pk_fma_f32 v[240:241], v[116:117], v[206:207], v[240:241] op_sel:[0,1,0] op_sel_hi:[1,1,1]
	v_pk_fma_f32 v[242:243], v[118:119], v[204:205], v[242:243] op_sel:[0,0,0] op_sel_hi:[1,0,1]
	v_pk_fma_f32 v[242:243], v[120:121], v[204:205], v[242:243] op_sel:[0,1,0] op_sel_hi:[1,1,1]
	v_pk_fma_f32 v[242:243], v[122:123], v[206:207], v[242:243] op_sel:[0,0,0] op_sel_hi:[1,0,1]
	v_pk_fma_f32 v[242:243], v[124:125], v[206:207], v[242:243] op_sel:[0,1,0] op_sel_hi:[1,1,1]
	v_fmac_f32_e32 v241, v126, v240
	v_pk_fma_f32 v[242:243], v[128:129], v[240:241], v[242:243] op_sel:[0,0,0] op_sel_hi:[1,0,1]
	v_pk_fma_f32 v[242:243], v[130:131], v[240:241], v[242:243] op_sel:[0,1,0] op_sel_hi:[1,1,1]
	v_fmac_f32_e32 v243, v127, v242
	v_cndmask_b32_e64 v200, v240, v84, s[98:99]
	v_cndmask_b32_e64 v201, v241, v85, s[98:99]
	v_cndmask_b32_e64 v202, v242, v86, s[98:99]
	v_cndmask_b32_e64 v203, v243, v87, s[98:99]
	v_mov_b32_e32 v252, v240
	v_mov_b32_e32 v253, v241
	v_mov_b32_e32 v254, v242
	v_mov_b32_e32 v255, v243
	v_mfma_f32_16x16x4_f32 v[208:211], v184, v200, v[208:211]
	v_mfma_f32_16x16x4_f32 v[212:215], v188, v200, v[212:215]
	v_mfma_f32_16x16x4_f32 v[216:219], v192, v200, v[216:219]
	v_mfma_f32_16x16x4_f32 v[220:223], v196, v200, v[220:223]
	v_permlane32_swap_b32_e32 v252, v254
	v_permlane32_swap_b32_e32 v253, v255
	v_mfma_f32_16x16x4_f32 v[208:211], v185, v201, v[208:211]
	v_mfma_f32_16x16x4_f32 v[212:215], v189, v201, v[212:215]
	v_mfma_f32_16x16x4_f32 v[216:219], v193, v201, v[216:219]
	v_mfma_f32_16x16x4_f32 v[220:223], v197, v201, v[220:223]
	v_mfma_f32_16x16x4_f32 v[208:211], v186, v202, v[208:211]
	v_mfma_f32_16x16x4_f32 v[212:215], v190, v202, v[212:215]
	v_mfma_f32_16x16x4_f32 v[216:219], v194, v202, v[216:219]
	v_mfma_f32_16x16x4_f32 v[220:223], v198, v202, v[220:223]
	v_mfma_f32_16x16x4_f32 v[208:211], v187, v203, v[208:211]
	v_mfma_f32_16x16x4_f32 v[212:215], v191, v203, v[212:215]
	v_mfma_f32_16x16x4_f32 v[216:219], v195, v203, v[216:219]
	v_mfma_f32_16x16x4_f32 v[220:223], v199, v203, v[220:223]
	v_mfma_f32_16x16x4_f32 v[248:251], v82, v252, v[240:243]
	v_mfma_f32_16x16x4_f32 v[248:251], v83, v253, v[248:251]
	s_waitcnt lgkmcnt(0)
	s_nop 4
	v_pk_mul_f32 v[208:209], v[208:209], v[88:89]
	v_pk_mul_f32 v[210:211], v[210:211], v[90:91]
	s_nop 0
	v_mfma_f32_16x16x4_f32 v[72:75], v140, v208, v[72:75]
	v_pk_mul_f32 v[212:213], v[212:213], v[92:93]
	v_mfma_f32_16x16x4_f32 v[244:247], v141, v209, 0
	v_pk_mul_f32 v[214:215], v[214:215], v[94:95]
	v_mfma_f32_16x16x4_f32 v[72:75], v142, v210, v[72:75]
	v_pk_mul_f32 v[216:217], v[216:217], v[96:97]
	v_mfma_f32_16x16x4_f32 v[244:247], v143, v211, v[244:247]
	v_pk_mul_f32 v[218:219], v[218:219], v[98:99]
	v_mfma_f32_16x16x4_f32 v[72:75], v144, v212, v[72:75]
	v_pk_mul_f32 v[220:221], v[220:221], v[100:101]
	v_mfma_f32_16x16x4_f32 v[244:247], v145, v213, v[244:247]
	v_pk_mul_f32 v[222:223], v[222:223], v[102:103]
	v_mfma_f32_16x16x4_f32 v[72:75], v146, v214, v[72:75]
	s_mov_b64 exec, s[98:99]
	ds_write_b32 v231, v248
	ds_write_b32 v231, v249 offset:256
	ds_write_b32 v231, v250 offset:512
	ds_write_b32 v231, v251 offset:768
	s_mov_b64 exec, -1
	ds_read_b128 v[184:187], v236 offset:14080
	ds_read_b128 v[188:191], v236 offset:15104
	v_mfma_f32_16x16x4_f32 v[244:247], v147, v215, v[244:247]
	ds_read_b128 v[192:195], v236 offset:16128
	ds_read_b128 v[196:199], v236 offset:17152
	v_mfma_f32_16x16x4_f32 v[72:75], v148, v216, v[72:75]
	ds_read_b64 v[80:81], v32
	ds_read_b64 v[82:83], v33
	ds_read_b32 v84, v230 offset:4096
	ds_read_b32 v85, v230 offset:4352
	v_mfma_f32_16x16x4_f32 v[244:247], v149, v217, v[244:247]
	ds_read_b32 v86, v230 offset:4608
	ds_read_b32 v87, v230 offset:4864
	ds_read_b32 v36, v239 offset:4096
	ds_read_b32 v37, v239 offset:4352
	v_mfma_f32_16x16x4_f32 v[72:75], v150, v218, v[72:75]
	ds_read_b128 v[88:91], v26
	ds_read_b128 v[92:95], v26 offset:1024
	ds_read_b128 v[96:99], v26 offset:2048
	ds_read_b128 v[100:103], v26 offset:3072
	v_mfma_f32_16x16x4_f32 v[244:247], v151, v219, v[244:247]
	ds_read_b32 v104, v29 offset:4
	ds_read_b32 v105, v29 offset:76
	ds_read_b64 v[106:107], v29 offset:8
	ds_read_b64 v[108:109], v29 offset:40
	v_mfma_f32_16x16x4_f32 v[72:75], v152, v220, v[72:75]
	ds_read_b32 v126, v31 offset:4
	ds_read_b32 v127, v31 offset:76
	ds_read_b64 v[128:129], v31 offset:8
	ds_read_b64 v[130:131], v31 offset:40
	v_mfma_f32_16x16x4_f32 v[244:247], v153, v221, v[244:247]
	ds_read_b64 v[110:111], v30
	ds_read_b64 v[112:113], v30 offset:32
	ds_read_b64 v[114:115], v30 offset:64
	ds_read_b64 v[116:117], v30 offset:96
	v_mfma_f32_16x16x4_f32 v[72:75], v154, v222, v[72:75]
	ds_read_b64 v[118:119], v30 offset:8
	ds_read_b64 v[120:121], v30 offset:40
	ds_read_b64 v[122:123], v30 offset:72
	ds_read_b64 v[124:125], v30 offset:104
	v_mfma_f32_16x16x4_f32 v[244:247], v155, v223, v[244:247]
	s_nop 9
	v_pk_add_f32 v[72:73], v[72:73], v[244:245]
	v_pk_add_f32 v[74:75], v[74:75], v[246:247]
	v_fmac_f32_e32 v73, v156, v72
	v_pk_fma_f32 v[74:75], v[158:159], v[72:73], v[74:75] op_sel:[0,0,0] op_sel_hi:[1,0,1]
	v_pk_fma_f32 v[74:75], v[160:161], v[72:73], v[74:75] op_sel:[0,1,0] op_sel_hi:[1,1,1]
	v_fmac_f32_e32 v75, v157, v74
	v_mov_b32_e32 v44, v72
	v_mov_b32_e32 v45, v73
	v_mov_b32_e32 v60, v74
	v_mov_b32_e32 v61, v75
	v_permlane16_swap_b32_e32 v204, v44
	v_permlane16_swap_b32_e32 v205, v45
	v_permlane16_swap_b32_e32 v206, v60
	v_permlane16_swap_b32_e32 v207, v61
	ds_read_b128 v[140:143], v226 offset:9984
	ds_read_b128 v[144:147], v226 offset:10048
	ds_read_b128 v[148:151], v226 offset:10112
	ds_read_b128 v[152:155], v226 offset:10176
	s_waitcnt lgkmcnt(7)
	v_mfma_f32_16x16x4_f32 v[240:243], v80, v36, 0
	v_mfma_f32_16x16x4_f32 v[240:243], v81, v37, v[240:243]
	v_pk_fma_f32 v[72:73], v[162:163], v[204:205], v[72:73] op_sel:[0,0,0] op_sel_hi:[1,0,1]
	v_pk_fma_f32 v[72:73], v[164:165], v[204:205], v[72:73] op_sel:[0,1,0] op_sel_hi:[1,1,1]
	v_pk_fma_f32 v[72:73], v[166:167], v[206:207], v[72:73] op_sel:[0,0,0] op_sel_hi:[1,0,1]
	v_pk_fma_f32 v[72:73], v[168:169], v[206:207], v[72:73] op_sel:[0,1,0] op_sel_hi:[1,1,1]
	v_pk_fma_f32 v[74:75], v[170:171], v[204:205], v[74:75] op_sel:[0,0,0] op_sel_hi:[1,0,1]
	v_pk_fma_f32 v[74:75], v[172:173], v[204:205], v[74:75] op_sel:[0,1,0] op_sel_hi:[1,1,1]
	v_pk_fma_f32 v[74:75], v[174:175], v[206:207], v[74:75] op_sel:[0,0,0] op_sel_hi:[1,0,1]
	v_pk_fma_f32 v[74:75], v[176:177], v[206:207], v[74:75] op_sel:[0,1,0] op_sel_hi:[1,1,1]
	v_fmac_f32_e32 v73, v178, v72
	v_pk_fma_f32 v[74:75], v[180:181], v[72:73], v[74:75] op_sel:[0,0,0] op_sel_hi:[1,0,1]
	v_pk_fma_f32 v[74:75], v[182:183], v[72:73], v[74:75] op_sel:[0,1,0] op_sel_hi:[1,1,1]
	v_fmac_f32_e32 v75, v179, v74
	v_cndmask_b32_e64 v200, v72, v136, s[98:99]
	v_cndmask_b32_e64 v201, v73, v137, s[98:99]
	v_cndmask_b32_e64 v202, v74, v138, s[98:99]
	v_cndmask_b32_e64 v203, v75, v139, s[98:99]
	v_mov_b32_e32 v252, v72
	v_mov_b32_e32 v253, v73
	v_mov_b32_e32 v254, v74
	v_mov_b32_e32 v255, v75
	v_mfma_f32_16x16x4_f32 v[208:211], v184, v200, v[208:211]
	v_mfma_f32_16x16x4_f32 v[212:215], v188, v200, v[212:215]
	v_mfma_f32_16x16x4_f32 v[216:219], v192, v200, v[216:219]
	v_mfma_f32_16x16x4_f32 v[220:223], v196, v200, v[220:223]
	v_permlane32_swap_b32_e32 v252, v254
	v_permlane32_swap_b32_e32 v253, v255
	v_mfma_f32_16x16x4_f32 v[208:211], v185, v201, v[208:211]
	v_mfma_f32_16x16x4_f32 v[212:215], v189, v201, v[212:215]
	v_mfma_f32_16x16x4_f32 v[216:219], v193, v201, v[216:219]
	v_mfma_f32_16x16x4_f32 v[220:223], v197, v201, v[220:223]
	v_mfma_f32_16x16x4_f32 v[208:211], v186, v202, v[208:211]
	v_mfma_f32_16x16x4_f32 v[212:215], v190, v202, v[212:215]
	v_mfma_f32_16x16x4_f32 v[216:219], v194, v202, v[216:219]
	v_mfma_f32_16x16x4_f32 v[220:223], v198, v202, v[220:223]
	v_mfma_f32_16x16x4_f32 v[208:211], v187, v203, v[208:211]
	v_mfma_f32_16x16x4_f32 v[212:215], v191, v203, v[212:215]
	v_mfma_f32_16x16x4_f32 v[216:219], v195, v203, v[216:219]
	v_mfma_f32_16x16x4_f32 v[220:223], v199, v203, v[220:223]
	v_mfma_f32_16x16x4_f32 v[248:251], v134, v252, v[72:75]
	v_mfma_f32_16x16x4_f32 v[248:251], v135, v253, v[248:251]
	s_waitcnt lgkmcnt(0)
	s_nop 4
	v_pk_mul_f32 v[208:209], v[208:209], v[140:141]
	v_pk_mul_f32 v[210:211], v[210:211], v[142:143]
	s_nop 0
	v_mfma_f32_16x16x4_f32 v[240:243], v88, v208, v[240:243]
	v_pk_mul_f32 v[212:213], v[212:213], v[144:145]
	v_mfma_f32_16x16x4_f32 v[244:247], v89, v209, 0
	v_pk_mul_f32 v[214:215], v[214:215], v[146:147]
	v_mfma_f32_16x16x4_f32 v[240:243], v90, v210, v[240:243]
	v_pk_mul_f32 v[216:217], v[216:217], v[148:149]
	v_mfma_f32_16x16x4_f32 v[244:247], v91, v211, v[244:247]
	v_pk_mul_f32 v[218:219], v[218:219], v[150:151]
	v_mfma_f32_16x16x4_f32 v[240:243], v92, v212, v[240:243]
	v_pk_mul_f32 v[220:221], v[220:221], v[152:153]
	v_mfma_f32_16x16x4_f32 v[244:247], v93, v213, v[244:247]
	v_pk_mul_f32 v[222:223], v[222:223], v[154:155]
	v_mfma_f32_16x16x4_f32 v[240:243], v94, v214, v[240:243]
	s_mov_b64 exec, s[98:99]
	ds_write_b32 v231, v248 offset:2048
	ds_write_b32 v231, v249 offset:2304
	ds_write_b32 v231, v250 offset:2560
	ds_write_b32 v231, v251 offset:2816
	s_mov_b64 exec, -1
	ds_read_b128 v[184:187], v27 offset:4096
	ds_read_b128 v[188:191], v27 offset:5120
	v_mfma_f32_16x16x4_f32 v[244:247], v95, v215, v[244:247]
	ds_read_b128 v[192:195], v27 offset:6144
	ds_read_b128 v[196:199], v27 offset:7168
	v_mfma_f32_16x16x4_f32 v[240:243], v96, v216, v[240:243]
	ds_read_b64 v[132:133], v32 offset:9984
	ds_read_b64 v[134:135], v33 offset:9984
	ds_read_b32 v136, v230 offset:6144
	ds_read_b32 v137, v230 offset:6400
	v_mfma_f32_16x16x4_f32 v[244:247], v97, v217, v[244:247]
	ds_read_b32 v138, v230 offset:6656
	ds_read_b32 v139, v230 offset:6912
	ds_read_b32 v38, v239 offset:6144
	ds_read_b32 v39, v239 offset:6400
	v_mfma_f32_16x16x4_f32 v[240:243], v98, v218, v[240:243]
	ds_read_b128 v[140:143], v26 offset:9984
	ds_read_b128 v[144:147], v26 offset:11008
	ds_read_b128 v[148:151], v26 offset:12032
	ds_read_b128 v[152:155], v26 offset:13056
	v_mfma_f32_16x16x4_f32 v[244:247], v99, v219, v[244:247]
	ds_read_b32 v156, v29 offset:9988
	ds_read_b32 v157, v29 offset:10060
	ds_read_b64 v[158:159], v29 offset:9992
	ds_read_b64 v[160:161], v29 offset:10024
	v_mfma_f32_16x16x4_f32 v[240:243], v100, v220, v[240:243]
	ds_read_b32 v178, v31 offset:9988
	ds_read_b32 v179, v31 offset:10060
	ds_read_b64 v[180:181], v31 offset:9992
	ds_read_b64 v[182:183], v31 offset:10024
	v_mfma_f32_16x16x4_f32 v[244:247], v101, v221, v[244:247]
	ds_read_b64 v[162:163], v30 offset:9984
	ds_read_b64 v[164:165], v30 offset:10016
	ds_read_b64 v[166:167], v30 offset:10048
	ds_read_b64 v[168:169], v30 offset:10080
	v_mfma_f32_16x16x4_f32 v[240:243], v102, v222, v[240:243]
	ds_read_b64 v[170:171], v30 offset:9992
	ds_read_b64 v[172:173], v30 offset:10024
	ds_read_b64 v[174:175], v30 offset:10056
	ds_read_b64 v[176:177], v30 offset:10088
	v_mfma_f32_16x16x4_f32 v[244:247], v103, v223, v[244:247]
	s_nop 9
	v_pk_add_f32 v[240:241], v[240:241], v[244:245]
	v_pk_add_f32 v[242:243], v[242:243], v[246:247]
	v_fmac_f32_e32 v241, v104, v240
	v_pk_fma_f32 v[242:243], v[106:107], v[240:241], v[242:243] op_sel:[0,0,0] op_sel_hi:[1,0,1]
	v_pk_fma_f32 v[242:243], v[108:109], v[240:241], v[242:243] op_sel:[0,1,0] op_sel_hi:[1,1,1]
	v_fmac_f32_e32 v243, v105, v242
	v_mov_b32_e32 v44, v240
	v_mov_b32_e32 v45, v241
	v_mov_b32_e32 v60, v242
	v_mov_b32_e32 v61, v243
	v_permlane16_swap_b32_e32 v204, v44
	v_permlane16_swap_b32_e32 v205, v45
	v_permlane16_swap_b32_e32 v206, v60
	v_permlane16_swap_b32_e32 v207, v61
	ds_read_b128 v[88:91], v28
	ds_read_b128 v[92:95], v28 offset:64
	ds_read_b128 v[96:99], v28 offset:128
	ds_read_b128 v[100:103], v28 offset:192
	s_waitcnt lgkmcnt(7)
	v_mfma_f32_16x16x4_f32 v[72:75], v132, v38, 0
	v_mfma_f32_16x16x4_f32 v[72:75], v133, v39, v[72:75]
	v_pk_fma_f32 v[240:241], v[110:111], v[204:205], v[240:241] op_sel:[0,0,0] op_sel_hi:[1,0,1]
	v_pk_fma_f32 v[240:241], v[112:113], v[204:205], v[240:241] op_sel:[0,1,0] op_sel_hi:[1,1,1]
	v_pk_fma_f32 v[240:241], v[114:115], v[206:207], v[240:241] op_sel:[0,0,0] op_sel_hi:[1,0,1]
	v_pk_fma_f32 v[240:241], v[116:117], v[206:207], v[240:241] op_sel:[0,1,0] op_sel_hi:[1,1,1]
	v_pk_fma_f32 v[242:243], v[118:119], v[204:205], v[242:243] op_sel:[0,0,0] op_sel_hi:[1,0,1]
	v_pk_fma_f32 v[242:243], v[120:121], v[204:205], v[242:243] op_sel:[0,1,0] op_sel_hi:[1,1,1]
	v_pk_fma_f32 v[242:243], v[122:123], v[206:207], v[242:243] op_sel:[0,0,0] op_sel_hi:[1,0,1]
	v_pk_fma_f32 v[242:243], v[124:125], v[206:207], v[242:243] op_sel:[0,1,0] op_sel_hi:[1,1,1]
	v_fmac_f32_e32 v241, v126, v240
	v_pk_fma_f32 v[242:243], v[128:129], v[240:241], v[242:243] op_sel:[0,0,0] op_sel_hi:[1,0,1]
	v_pk_fma_f32 v[242:243], v[130:131], v[240:241], v[242:243] op_sel:[0,1,0] op_sel_hi:[1,1,1]
	v_fmac_f32_e32 v243, v127, v242
	v_cndmask_b32_e64 v200, v240, v84, s[98:99]
	v_cndmask_b32_e64 v201, v241, v85, s[98:99]
	v_cndmask_b32_e64 v202, v242, v86, s[98:99]
	v_cndmask_b32_e64 v203, v243, v87, s[98:99]
	v_mov_b32_e32 v252, v240
	v_mov_b32_e32 v253, v241
	v_mov_b32_e32 v254, v242
	v_mov_b32_e32 v255, v243
	v_mfma_f32_16x16x4_f32 v[208:211], v184, v200, v[208:211]
	v_mfma_f32_16x16x4_f32 v[212:215], v188, v200, v[212:215]
	v_mfma_f32_16x16x4_f32 v[216:219], v192, v200, v[216:219]
	v_mfma_f32_16x16x4_f32 v[220:223], v196, v200, v[220:223]
	v_permlane32_swap_b32_e32 v252, v254
	v_permlane32_swap_b32_e32 v253, v255
	v_mfma_f32_16x16x4_f32 v[208:211], v185, v201, v[208:211]
	v_mfma_f32_16x16x4_f32 v[212:215], v189, v201, v[212:215]
	v_mfma_f32_16x16x4_f32 v[216:219], v193, v201, v[216:219]
	v_mfma_f32_16x16x4_f32 v[220:223], v197, v201, v[220:223]
	v_mfma_f32_16x16x4_f32 v[208:211], v186, v202, v[208:211]
	v_mfma_f32_16x16x4_f32 v[212:215], v190, v202, v[212:215]
	v_mfma_f32_16x16x4_f32 v[216:219], v194, v202, v[216:219]
	v_mfma_f32_16x16x4_f32 v[220:223], v198, v202, v[220:223]
	v_mfma_f32_16x16x4_f32 v[208:211], v187, v203, v[208:211]
	v_mfma_f32_16x16x4_f32 v[212:215], v191, v203, v[212:215]
	v_mfma_f32_16x16x4_f32 v[216:219], v195, v203, v[216:219]
	v_mfma_f32_16x16x4_f32 v[220:223], v199, v203, v[220:223]
	v_mfma_f32_16x16x4_f32 v[248:251], v82, v252, v[240:243]
	v_mfma_f32_16x16x4_f32 v[248:251], v83, v253, v[248:251]
	s_waitcnt lgkmcnt(0)
	s_nop 4
	v_pk_mul_f32 v[208:209], v[208:209], v[88:89]
	v_pk_mul_f32 v[210:211], v[210:211], v[90:91]
	s_nop 0
	v_mfma_f32_16x16x4_f32 v[72:75], v140, v208, v[72:75]
	v_pk_mul_f32 v[212:213], v[212:213], v[92:93]
	v_mfma_f32_16x16x4_f32 v[244:247], v141, v209, 0
	v_pk_mul_f32 v[214:215], v[214:215], v[94:95]
	v_mfma_f32_16x16x4_f32 v[72:75], v142, v210, v[72:75]
	v_pk_mul_f32 v[216:217], v[216:217], v[96:97]
	v_mfma_f32_16x16x4_f32 v[244:247], v143, v211, v[244:247]
	v_pk_mul_f32 v[218:219], v[218:219], v[98:99]
	v_mfma_f32_16x16x4_f32 v[72:75], v144, v212, v[72:75]
	v_pk_mul_f32 v[220:221], v[220:221], v[100:101]
	v_mfma_f32_16x16x4_f32 v[244:247], v145, v213, v[244:247]
	v_pk_mul_f32 v[222:223], v[222:223], v[102:103]
	v_mfma_f32_16x16x4_f32 v[72:75], v146, v214, v[72:75]
	s_mov_b64 exec, s[98:99]
	ds_write_b32 v231, v248 offset:4096
	ds_write_b32 v231, v249 offset:4352
	ds_write_b32 v231, v250 offset:4608
	ds_write_b32 v231, v251 offset:4864
	s_mov_b64 exec, -1
	ds_read_b128 v[184:187], v27 offset:14080
	ds_read_b128 v[188:191], v27 offset:15104
	v_mfma_f32_16x16x4_f32 v[244:247], v147, v215, v[244:247]
	ds_read_b128 v[192:195], v27 offset:16128
	ds_read_b128 v[196:199], v27 offset:17152
	v_mfma_f32_16x16x4_f32 v[72:75], v148, v216, v[72:75]
	v_mfma_f32_16x16x4_f32 v[244:247], v149, v217, v[244:247]
	v_mfma_f32_16x16x4_f32 v[72:75], v150, v218, v[72:75]
	v_mfma_f32_16x16x4_f32 v[244:247], v151, v219, v[244:247]
	v_mfma_f32_16x16x4_f32 v[72:75], v152, v220, v[72:75]
	v_mfma_f32_16x16x4_f32 v[244:247], v153, v221, v[244:247]
	v_mfma_f32_16x16x4_f32 v[72:75], v154, v222, v[72:75]
	v_mfma_f32_16x16x4_f32 v[244:247], v155, v223, v[244:247]
	s_nop 9
	v_pk_add_f32 v[72:73], v[72:73], v[244:245]
	v_pk_add_f32 v[74:75], v[74:75], v[246:247]
	v_fmac_f32_e32 v73, v156, v72
	v_pk_fma_f32 v[74:75], v[158:159], v[72:73], v[74:75] op_sel:[0,0,0] op_sel_hi:[1,0,1]
	v_pk_fma_f32 v[74:75], v[160:161], v[72:73], v[74:75] op_sel:[0,1,0] op_sel_hi:[1,1,1]
	v_fmac_f32_e32 v75, v157, v74
	v_mov_b32_e32 v44, v72
	v_mov_b32_e32 v45, v73
	v_mov_b32_e32 v60, v74
	v_mov_b32_e32 v61, v75
	v_permlane16_swap_b32_e32 v204, v44
	v_permlane16_swap_b32_e32 v205, v45
	v_permlane16_swap_b32_e32 v206, v60
	v_permlane16_swap_b32_e32 v207, v61
	ds_read_b128 v[140:143], v28 offset:9984
	ds_read_b128 v[144:147], v28 offset:10048
	ds_read_b128 v[148:151], v28 offset:10112
	ds_read_b128 v[152:155], v28 offset:10176
	v_pk_fma_f32 v[72:73], v[162:163], v[204:205], v[72:73] op_sel:[0,0,0] op_sel_hi:[1,0,1]
	v_pk_fma_f32 v[72:73], v[164:165], v[204:205], v[72:73] op_sel:[0,1,0] op_sel_hi:[1,1,1]
	v_pk_fma_f32 v[72:73], v[166:167], v[206:207], v[72:73] op_sel:[0,0,0] op_sel_hi:[1,0,1]
	v_pk_fma_f32 v[72:73], v[168:169], v[206:207], v[72:73] op_sel:[0,1,0] op_sel_hi:[1,1,1]
	v_pk_fma_f32 v[74:75], v[170:171], v[204:205], v[74:75] op_sel:[0,0,0] op_sel_hi:[1,0,1]
	v_pk_fma_f32 v[74:75], v[172:173], v[204:205], v[74:75] op_sel:[0,1,0] op_sel_hi:[1,1,1]
	v_pk_fma_f32 v[74:75], v[174:175], v[206:207], v[74:75] op_sel:[0,0,0] op_sel_hi:[1,0,1]
	v_pk_fma_f32 v[74:75], v[176:177], v[206:207], v[74:75] op_sel:[0,1,0] op_sel_hi:[1,1,1]
	v_fmac_f32_e32 v73, v178, v72
	v_pk_fma_f32 v[74:75], v[180:181], v[72:73], v[74:75] op_sel:[0,0,0] op_sel_hi:[1,0,1]
	v_pk_fma_f32 v[74:75], v[182:183], v[72:73], v[74:75] op_sel:[0,1,0] op_sel_hi:[1,1,1]
	v_fmac_f32_e32 v75, v179, v74
	v_cndmask_b32_e64 v200, v72, v136, s[98:99]
	v_cndmask_b32_e64 v201, v73, v137, s[98:99]
	v_cndmask_b32_e64 v202, v74, v138, s[98:99]
	v_cndmask_b32_e64 v203, v75, v139, s[98:99]
	v_mov_b32_e32 v252, v72
	v_mov_b32_e32 v253, v73
	v_mov_b32_e32 v254, v74
	v_mov_b32_e32 v255, v75
	s_waitcnt lgkmcnt(3)
	v_mfma_f32_16x16x4_f32 v[208:211], v184, v200, v[208:211]
	v_mfma_f32_16x16x4_f32 v[212:215], v188, v200, v[212:215]
	v_mfma_f32_16x16x4_f32 v[216:219], v192, v200, v[216:219]
	v_mfma_f32_16x16x4_f32 v[220:223], v196, v200, v[220:223]
	v_permlane32_swap_b32_e32 v252, v254
	v_permlane32_swap_b32_e32 v253, v255
	v_mfma_f32_16x16x4_f32 v[208:211], v185, v201, v[208:211]
	v_mfma_f32_16x16x4_f32 v[212:215], v189, v201, v[212:215]
	v_mfma_f32_16x16x4_f32 v[216:219], v193, v201, v[216:219]
	v_mfma_f32_16x16x4_f32 v[220:223], v197, v201, v[220:223]
	v_mfma_f32_16x16x4_f32 v[208:211], v186, v202, v[208:211]
	v_mfma_f32_16x16x4_f32 v[212:215], v190, v202, v[212:215]
	v_mfma_f32_16x16x4_f32 v[216:219], v194, v202, v[216:219]
	v_mfma_f32_16x16x4_f32 v[220:223], v198, v202, v[220:223]
	v_mfma_f32_16x16x4_f32 v[208:211], v187, v203, v[208:211]
	v_mfma_f32_16x16x4_f32 v[212:215], v191, v203, v[212:215]
	v_mfma_f32_16x16x4_f32 v[216:219], v195, v203, v[216:219]
	v_mfma_f32_16x16x4_f32 v[220:223], v199, v203, v[220:223]
	v_mfma_f32_16x16x4_f32 v[248:251], v134, v252, v[72:75]
	v_mfma_f32_16x16x4_f32 v[248:251], v135, v253, v[248:251]
	s_nop 4
	v_pk_mul_f32 v[208:209], v[208:209], v[140:141]
	v_pk_mul_f32 v[210:211], v[210:211], v[142:143]
	s_waitcnt lgkmcnt(0)
	v_pk_mul_f32 v[212:213], v[212:213], v[144:145]
	v_pk_mul_f32 v[214:215], v[214:215], v[146:147]
	v_pk_mul_f32 v[216:217], v[216:217], v[148:149]
	v_pk_mul_f32 v[218:219], v[218:219], v[150:151]
	v_pk_mul_f32 v[220:221], v[220:221], v[152:153]
	v_pk_mul_f32 v[222:223], v[222:223], v[154:155]
	s_mov_b64 exec, s[98:99]
	ds_write_b32 v231, v248 offset:6144
	ds_write_b32 v231, v249 offset:6400
	ds_write_b32 v231, v250 offset:6656
	ds_write_b32 v231, v251 offset:6912
	s_mov_b64 exec, -1
	s_branch .LBB0_655

.Lmy_ck_drE_h:
	s_waitcnt lgkmcnt(0)
	s_bfe_u32 s96, s62, 0x20006
	s_and_b32 s97, s96, 1
	s_mul_i32 s97, s97, 0x2700
	s_mov_b32 s101, 0x1c000
	s_mov_b32 s100, 0x6100
	s_bitcmp0_b32 s65, 0
	s_cselect_b32 s101, 0xe000, s101
	s_cselect_b32 s100, 0x4e00, s100
	s_cmp_gt_u32 s96, 1
	s_cselect_b32 s100, s100, 0
	s_add_i32 s97, s97, s101
	s_add_i32 s97, s97, s100
	s_mov_b32 s96, s97
	v_and_b32_e32 v72, 3, v233
	v_lshrrev_b32_e32 v73, 2, v233
	v_lshlrev_b32_e32 v72, 2, v72
	v_lshl_add_u32 v72, v73, 8, v72
	v_lshl_add_u32 v72, v234, 6, v72
	s_add_i32 s97, s96, 0x1000
	v_add_u32_e32 v78, s97, v72
	v_xor_b32_e32 v79, v224, v234
	v_lshl_add_u32 v79, v79, 4, s96
	ds_read_b128 v[96:99], v79
	ds_read_b128 v[100:103], v79 offset:1024
	ds_read_b128 v[104:107], v79 offset:2048
	ds_read_b128 v[108:111], v79 offset:3072
	ds_read_b32 v80, v78
	ds_read_b32 v81, v78 offset:16
	ds_read_b32 v82, v78 offset:32
	ds_read_b32 v83, v78 offset:48
	ds_read_b32 v84, v78 offset:1024
	ds_read_b32 v85, v78 offset:1040
	ds_read_b32 v86, v78 offset:1056
	ds_read_b32 v87, v78 offset:1072
	ds_read_b32 v88, v78 offset:2048
	ds_read_b32 v89, v78 offset:2064
	ds_read_b32 v90, v78 offset:2080
	ds_read_b32 v91, v78 offset:2096
	ds_read_b32 v92, v78 offset:3072
	ds_read_b32 v93, v78 offset:3088
	ds_read_b32 v94, v78 offset:3104
	ds_read_b32 v95, v78 offset:3120
	v_lshl_add_u32 v74, v224, 2, s96
	ds_write_b32 v74, v235 offset:9728
	v_add_u32_e32 v75, -1, v233
	v_mov_b32_e32 v76, -1
	v_cndmask_b32_e64 v75, v76, v75, s[98:99]
	v_cmp_lt_u32_e64 s[100:101], 7, v233
	v_add_u32_e32 v76, -8, v233
	v_and_b32_e32 v77, 1, v234
	v_cndmask_b32_e64 v75, v75, v76, s[100:101]
	v_lshlrev_b32_e32 v77, 2, v77
	v_sub_u32_e32 v76, v75, v77
	v_lshlrev_b32_e32 v77, 2, v234
	v_sub_u32_e32 v77, v233, v77
	v_add_u32_e32 v77, -1, v77
	s_waitcnt lgkmcnt(10)
	v_mfma_f32_16x16x4_f32 v[244:247], v80, v96, 0
	v_mfma_f32_16x16x4_f32 v[240:243], v81, v97, 0
	v_mfma_f32_16x16x4_f32 v[244:247], v82, v98, v[244:247]
	v_mfma_f32_16x16x4_f32 v[240:243], v83, v99, v[240:243]
	v_mfma_f32_16x16x4_f32 v[244:247], v84, v100, v[244:247]
	v_mfma_f32_16x16x4_f32 v[240:243], v85, v101, v[240:243]
	v_mfma_f32_16x16x4_f32 v[244:247], v86, v102, v[244:247]
	s_waitcnt lgkmcnt(2)
	v_mfma_f32_16x16x4_f32 v[240:243], v87, v103, v[240:243]
	v_mfma_f32_16x16x4_f32 v[244:247], v88, v104, v[244:247]
	v_mfma_f32_16x16x4_f32 v[240:243], v89, v105, v[240:243]
	v_mfma_f32_16x16x4_f32 v[244:247], v90, v106, v[244:247]
	v_mfma_f32_16x16x4_f32 v[240:243], v91, v107, v[240:243]
	v_mfma_f32_16x16x4_f32 v[244:247], v92, v108, v[244:247]
	v_mfma_f32_16x16x4_f32 v[240:243], v93, v109, v[240:243]
	v_mfma_f32_16x16x4_f32 v[244:247], v94, v110, v[244:247]
	s_waitcnt lgkmcnt(1)
	v_mfma_f32_16x16x4_f32 v[240:243], v95, v111, v[240:243]
	s_nop 9
	v_add_f32_e32 v244, v244, v240
	v_add_f32_e32 v245, v245, v241
	v_add_f32_e32 v246, v246, v242
	v_add_f32_e32 v247, v247, v243
	v_cmp_le_i32_e64 s[96:97], 0, v76
	v_cmp_le_i32_e64 s[100:101], 1, v76
	s_nop 0
	v_cndmask_b32_e64 v128, 0, v244, s[96:97]
	v_cndmask_b32_e64 v129, 0, v245, s[100:101]
	v_cmp_le_i32_e64 s[96:97], 2, v76
	v_cmp_le_i32_e64 s[100:101], 3, v76
	s_nop 0
	v_cndmask_b32_e64 v130, 0, v246, s[96:97]
	v_cndmask_b32_e64 v131, 0, v247, s[100:101]
	s_bfe_u32 s96, s62, 0x20006
	s_and_b32 s97, s96, 1
	s_mul_i32 s97, s97, 0x2700
	s_mov_b32 s101, 0x1c000
	s_mov_b32 s100, 0x6100
	s_bitcmp0_b32 s65, 0
	s_cselect_b32 s101, 0xe000, s101
	s_cselect_b32 s100, 0x4e00, s100
	s_cmp_gt_u32 s96, 1
	s_cselect_b32 s100, s100, 0
	s_add_i32 s97, s97, s101
	s_add_i32 s97, s97, s100
	v_xor_b32_e32 v74, v224, v234
	v_lshl_add_u32 v74, v74, 4, s97
	ds_write_b128 v74, v[128:131] offset:8448
	v_lshlrev_b32_e32 v75, 7, v234
	v_lshl_add_u32 v75, v233, 2, v75
	v_add_u32_e32 v75, s97, v75
	v_cmp_le_i32_e64 s[96:97], 0, v77
	v_cmp_le_i32_e64 s[100:101], 1, v77
	s_nop 0
	v_cndmask_b32_e64 v132, 0, v244, s[96:97]
	v_cndmask_b32_e64 v133, 0, v245, s[100:101]
	v_cmp_le_i32_e64 s[96:97], 2, v77
	v_cmp_le_i32_e64 s[100:101], 3, v77
	s_nop 0
	v_cndmask_b32_e64 v134, 0, v246, s[96:97]
	v_cndmask_b32_e64 v135, 0, v247, s[100:101]
	s_mov_b64 exec, 0x00ff00ff
	ds_write_b32 v75, v132 offset:9472
	ds_write_b32 v75, v133 offset:9504
	ds_write_b32 v75, v134 offset:9536
	ds_write_b32 v75, v135 offset:9568
	s_mov_b64 exec, -1
	s_setprio 0
	s_branch .LBB0_655
	s_nop 0
	s_nop 0
	s_nop 0
	s_nop 0
	s_nop 0
	s_nop 0
	s_nop 0
	s_nop 0
	s_nop 0
	s_nop 0
	s_nop 0
	s_nop 0
	s_nop 0
	s_nop 0
	s_nop 0
	s_nop 0
	s_nop 0
	s_nop 0
	s_nop 0
	s_nop 0
	s_nop 0
	s_nop 0
	s_nop 0
	s_nop 0
	s_nop 0
	s_nop 0
	s_nop 0
	s_nop 0
	s_nop 0
	s_nop 0
	s_nop 0
	s_nop 0
	s_nop 0
	s_nop 0
	s_nop 0
	s_nop 0
	s_nop 0
	s_nop 0
	s_nop 0
	s_nop 0
	s_nop 0
	s_nop 0
	s_nop 0
	s_nop 0
	s_nop 0
	s_nop 0
	s_nop 0
	s_nop 0
	s_nop 0
	s_nop 0
	s_nop 0
	s_nop 0
